# pass 2: Y computed transposed (MFMA operands swapped) so 4 dwordx2 stores replace 16 short stores per chunk
# speedup vs baseline: 1.0035x; 1.0035x over previous
.LBB0_537:
	s_or_b64 exec, exec, s[34:35]
	v_mul_f32_e32 v84, v84, v198
	v_mul_f32_e32 v85, v85, v199
	v_mul_f32_e32 v0, v86, v232
	v_mul_f32_e32 v1, v87, v233
	v_lshlrev_b32_e32 v86, 3, v238
	v_cvt_pk_bf16_f32 v90, v84, v85
	v_mul_f32_e32 v84, v196, v88
	v_mul_f32_e32 v85, v197, v89
	v_and_b32_e32 v132, 24, v86
	v_cvt_pk_bf16_f32 v86, v84, v85
	v_mul_f32_e32 v84, v210, v208
	v_mul_f32_e32 v85, v211, v209
	v_mul_f32_e32 v88, v130, v192
	v_mul_f32_e32 v89, v131, v193
	v_cvt_pk_bf16_f32 v99, v84, v85
	v_cvt_pk_bf16_f32 v98, v88, v89
	v_mul_f32_e32 v84, v186, v148
	v_mul_f32_e32 v85, v187, v149
	v_mul_f32_e32 v88, v184, v146
	v_mul_f32_e32 v89, v185, v147
	v_cvt_pk_bf16_f32 v97, v84, v85
	v_cvt_pk_bf16_f32 v96, v88, v89
	s_waitcnt lgkmcnt(0)
	v_cvt_pk_bf16_f32 v91, v0, v1
	v_mul_f32_e32 v0, v230, v92
	v_mul_f32_e32 v1, v231, v93
	v_mfma_f32_16x16x32_bf16 v[92:95], v[104:107], v[96:99], 0
	v_cvt_pk_bf16_f32 v87, v0, v1
	v_mul_f32_e32 v0, v224, v222
	v_mul_f32_e32 v1, v225, v223
	v_mul_f32_e32 v84, v220, v216
	v_mul_f32_e32 v85, v221, v217
	v_cvt_pk_bf16_f32 v89, v0, v1
	v_cvt_pk_bf16_f32 v88, v84, v85
	v_mfma_f32_16x16x32_bf16 v[126:129], v[100:103], v[96:99], 0
	v_mul_f32_e64 v0, v218, v134
	v_mul_f32_e64 v1, v219, v135
	v_mul_f32_e32 v84, v182, v120
	v_mul_f32_e32 v85, v183, v121
	v_lshlrev_b32_e32 v150, 2, v246
	v_mfma_f32_16x16x32_bf16 v[122:125], v[116:119], v[88:91], v[92:95]
	v_lshrrev_b32_e32 v2, 2, v237
	v_cvt_pk_bf16_f32 v84, v84, v85
	v_cvt_pk_bf16_f32 v85, v0, v1
	v_mfma_f32_16x16x32_bf16 v[92:95], v[96:99], v[100:103], 0
	v_mul_f32_e64 v0, v190, v110
	v_mul_f32_e64 v1, v191, v111
	v_mul_f32_e32 v120, v188, v108
	v_mul_f32_e32 v121, v189, v109
	v_or_b32_e32 v2, v150, v2
	v_mfma_f32_16x16x32_bf16 v[108:111], v[88:91], v[112:115], v[92:95]
	v_mul_u32_u24_e32 v133, 0x90, v2
	v_cmp_eq_u32_e64 s[42:43], v150, v237
	v_or_b32_e32 v2, 1, v150
	v_mfma_f32_16x16x32_bf16 v[126:129], v[112:115], v[88:91], v[126:129]
	v_cvt_pk_bf16_f32 v95, v0, v1
	v_mul_f32_e32 v0, v144, v138
	v_mul_f32_e32 v1, v145, v139
	v_mul_f32_e32 v92, v142, v140
	v_mul_f32_e32 v93, v143, v141
	v_cmp_lt_u32_e64 s[40:41], v237, v150
	v_cndmask_b32_e64 v131, 0, 1.0, s[42:43]
	v_cmp_lt_u32_e64 s[42:43], v2, v237
	v_cvt_pk_bf16_f32 v94, v120, v121
	v_cvt_pk_bf16_f32 v92, v92, v93
	v_cvt_pk_bf16_f32 v93, v0, v1
	v_cndmask_b32_e64 v1, 0, v108, s[40:41]
	v_cndmask_b32_e64 v108, 0, v123, s[42:43]
	v_cndmask_b32_e64 v134, 0, v127, s[42:43]
	v_cmp_eq_u32_e64 s[42:43], v2, v237
	v_or_b32_e32 v2, 2, v150
	v_mfma_f32_16x16x32_bf16 v[100:103], v[100:103], v[92:95], 0
	v_cndmask_b32_e64 v135, 0, 1.0, s[42:43]
	v_cmp_lt_u32_e64 s[42:43], v2, v237
	v_cmp_lt_u32_e64 s[44:45], v237, v2
	v_cmp_lt_u32_e32 vcc, v150, v237
	v_cndmask_b32_e64 v121, 0, v124, s[42:43]
	v_cndmask_b32_e64 v136, 0, v128, s[42:43]
	v_cmp_eq_u32_e64 s[42:43], v2, v237
	v_or_b32_e32 v2, 3, v150
	v_cndmask_b32_e32 v130, 0, v126, vcc
	v_cndmask_b32_e64 v137, 0, 1.0, s[42:43]
	v_cmp_lt_u32_e64 s[42:43], v2, v237
	v_mfma_f32_16x16x32_bf16 v[100:103], v[112:115], v[84:87], v[100:103]
	v_cvt_pk_bf16_f32 v112, v130, v134
	v_cndmask_b32_e64 v138, 0, v129, s[42:43]
	v_cvt_pk_bf16_f32 v113, v136, v138
	v_mov_b32_e32 v114, v3
	v_mov_b32_e32 v115, v3
	v_cmp_lt_u32_e64 s[46:47], v237, v2
	v_cndmask_b32_e32 v0, 0, v122, vcc
	v_cndmask_b32_e64 v109, v109, 0, vcc
	v_cndmask_b32_e64 v110, 0, v110, s[44:45]
	v_cndmask_b32_e64 v111, 0, v111, s[46:47]
	v_cndmask_b32_e64 v122, 0, v125, s[42:43]
	v_cmp_eq_u32_e64 s[42:43], v2, v237
	v_cvt_pk_bf16_f32 v120, v0, v108
	v_cvt_pk_bf16_f32 v0, v1, v109
	v_cvt_pk_bf16_f32 v1, v110, v111
	v_mov_b32_e32 v2, v3
	v_mfma_f32_16x16x32_bf16 v[104:107], v[104:107], v[92:95], 0
	v_cvt_pk_bf16_f32 v121, v121, v122
	v_cndmask_b32_e64 v140, v100, 0, s[40:41]
	v_mov_b32_e32 v124, v3
	v_mfma_f32_16x16x32_bf16 v[108:111], v[112:115], v[0:3], 0
	v_mov_b32_e32 v125, v3
	v_cndmask_b32_e32 v141, 0, v101, vcc
	v_cndmask_b32_e64 v143, v102, 0, s[44:45]
	v_mfma_f32_16x16x32_bf16 v[104:107], v[116:119], v[84:87], v[104:107]
	v_cndmask_b32_e64 v139, 0, 1.0, s[42:43]
	v_mfma_f32_16x16x32_bf16 v[116:119], v[0:3], v[112:115], 0
	s_nop 1
	v_cvt_pk_bf16_f32 v0, v108, v109
	v_cvt_pk_bf16_f32 v1, v110, v111
	s_nop 1
	v_cndmask_b32_e64 v104, v104, 0, s[40:41]
	v_cndmask_b32_e32 v100, 0, v105, vcc
	v_cndmask_b32_e64 v111, v103, 0, s[46:47]
	v_cvt_pk_bf16_f32 v122, v116, v117
	v_cvt_pk_bf16_f32 v123, v118, v119
	v_cvt_pk_bf16_f32 v108, v104, v100
	v_mfma_f32_16x16x32_bf16 v[112:115], v[0:3], v[112:115], 0
	v_cndmask_b32_e64 v142, v106, 0, s[44:45]
	v_cndmask_b32_e64 v109, v107, 0, s[46:47]
	v_mov_b32_e32 v106, v3
	v_mfma_f32_16x16x32_bf16 v[100:103], v[0:3], v[122:125], 0
	v_mov_b32_e32 v107, v3
	v_cvt_pk_bf16_f32 v109, v142, v109
	v_cvt_pk_bf16_f32 v110, v140, v141
	v_mfma_f32_16x16x32_bf16 v[126:129], v[122:125], v[0:3], 0
	v_sub_f32_e32 v1, v135, v134
	s_nop 2
	v_cvt_pk_bf16_f32 v100, v100, v101
	v_cvt_pk_bf16_f32 v101, v102, v103
	v_mov_b32_e32 v102, v3
	v_mov_b32_e32 v103, v3
	v_cvt_pk_bf16_f32 v104, v126, v127
	v_cvt_pk_bf16_f32 v105, v128, v129
	v_sub_f32_e32 v0, v131, v130
	v_sub_f32_e32 v123, v139, v138
	v_mfma_f32_16x16x32_bf16 v[100:103], v[100:103], v[104:107], 0
	v_sub_f32_e32 v122, v137, v136
	v_add_f32_e32 v118, v118, v122
	v_add_f32_e32 v119, v119, v123
	v_add_f32_e32 v0, v116, v0
	v_add_f32_e32 v1, v117, v1
	v_sub_f32_e32 v115, v119, v115
	v_sub_f32_e32 v114, v118, v114
	v_sub_f32_e32 v113, v1, v113
	v_sub_f32_e32 v112, v0, v112
	v_cvt_pk_bf16_f32 v0, v112, v113
	v_cvt_pk_bf16_f32 v1, v114, v115
	v_cvt_pk_bf16_f32 v111, v143, v111
	v_mov_b32_e32 v122, v3
	v_mfma_f32_16x16x32_bf16 v[104:107], v[104:107], v[0:3], v[112:115]
	v_cvt_pk_bf16_f32 v0, v100, v101
	v_cvt_pk_bf16_f32 v1, v102, v103
	v_mov_b32_e32 v102, v3
	v_mov_b32_e32 v103, v3
	v_mov_b32_e32 v123, v3
	s_nop 2
	v_cvt_pk_bf16_f32 v100, v104, v105
	v_cvt_pk_bf16_f32 v101, v106, v107
	s_nop 1
	v_mfma_f32_16x16x32_bf16 v[100:103], v[0:3], v[100:103], v[104:107]
	v_add3_u32 v1, v133, v132, s33
	s_nop 6
	v_cvt_pk_bf16_f32 v0, v100, v101
	ds_read_b64_tr_b16 v[144:145], v1 offset:18944
	ds_read_b64_tr_b16 v[148:149], v1 offset:18976
	ds_read_b64_tr_b16 v[128:129], v1 offset:19008
	ds_read_b64_tr_b16 v[100:101], v1 offset:19040
	ds_read_b64_tr_b16 v[124:125], v1 offset:21248
	ds_read_b64_tr_b16 v[116:117], v1 offset:21280
	ds_read_b64_tr_b16 v[112:113], v1 offset:21312
	ds_read_b64_tr_b16 v[104:105], v1 offset:21344
	ds_read_b64_tr_b16 v[126:127], v1 offset:23552
	ds_read_b64_tr_b16 v[118:119], v1 offset:23584
	ds_read_b64_tr_b16 v[114:115], v1 offset:23616
	ds_read_b64_tr_b16 v[106:107], v1 offset:23648
	v_cvt_pk_bf16_f32 v1, v102, v103
	s_setprio 1
	v_cvt_pk_bf16_f32 v130, v16, v17
	v_cvt_pk_bf16_f32 v131, v18, v19
	v_cvt_pk_bf16_f32 v132, v28, v29
	v_cvt_pk_bf16_f32 v133, v30, v31
	v_cvt_pk_bf16_f32 v134, v32, v33
	v_cvt_pk_bf16_f32 v135, v34, v35
	v_mfma_f32_16x16x32_bf16 v[138:141], v[96:99], v[130:133], 0
	v_cvt_pk_bf16_f32 v136, v56, v57
	v_cvt_pk_bf16_f32 v137, v58, v59
	v_mov_b32_e32 v146, v3
	v_mov_b32_e32 v147, v3
	v_mfma_f32_16x16x32_bf16 v[138:141], v[88:91], v[134:137], v[138:141]
	v_add_u32_e32 v182, s70, v237
	v_sub_u32_e32 v183, s54, v237
	v_add_u32_e32 v182, -16, v182
	v_add_u32_e32 v183, 3, v183
	v_cndmask_b32_e64 v180, v183, v182, s[38:39]
	v_ashrrev_i32_e32 v181, 31, v180
	v_lshl_add_u64 v[180:181], s[20:21], 0, v[180:181]
	v_lshlrev_b64 v[180:181], 11, v[180:181]
	v_lshlrev_b32_e32 v182, 3, v246
	v_or_b32_e32 v180, v180, v182
	v_lshl_add_u64 v[180:181], v[154:155], 0, v[180:181]

	v_cvt_pk_bf16_f32 v188, v4, v5
	s_waitcnt lgkmcnt(11)
	v_mfma_f32_16x16x32_bf16 v[138:141], v[120:123], v[144:147], v[138:141]
	v_cvt_pk_bf16_f32 v189, v6, v7
	v_cvt_pk_bf16_f32 v190, v20, v21
	v_cvt_pk_bf16_f32 v191, v22, v23
	v_mfma_f32_16x16x32_bf16 v[130:133], v[130:133], v[92:95], 0

	s_nop 2
	s_nop 0
	v_cvt_pk_bf16_f32 v138, v138, v139
	v_cvt_pk_bf16_f32 v139, v140, v141
	v_mov_b32_e32 v140, v3
	v_mov_b32_e32 v141, v3
	v_mfma_f32_16x16x32_bf16 v[130:133], v[134:137], v[84:87], v[130:133]


	s_nop 0
	v_mfma_f32_16x16x32_bf16 v[138:141], v[0:3], v[138:141], 0


	s_nop 2
	s_nop 4
	v_xor_b32_e32 v139, 0x80000000, v139
	v_xor_b32_e32 v138, 0x80000000, v138
	v_cvt_pk_bf16_f32 v146, v138, v139
	v_xor_b32_e32 v138, 0x80000000, v140
	v_xor_b32_e32 v139, 0x80000000, v141
	v_cvt_pk_bf16_f32 v147, v138, v139
	v_mfma_f32_16x16x32_bf16 v[196:199], v[96:99], v[188:191], 0


	v_cvt_pk_bf16_f32 v192, v36, v37
	v_mfma_f32_16x16x32_bf16 v[130:133], v[144:147], v[108:111], v[130:133]
	v_cvt_pk_bf16_f32 v193, v38, v39
	v_cvt_pk_bf16_f32 v194, v48, v49
	v_cvt_pk_bf16_f32 v195, v50, v51
	v_mov_b32_e32 v150, v3
	v_mov_b32_e32 v151, v3
	s_nop 2
	v_cvt_pk_bf16_f32 v130, v130, v131
	v_cvt_pk_bf16_f32 v131, v132, v133
	global_store_dwordx2 v[180:181], v[130:131], off


	v_mfma_f32_16x16x32_bf16 v[196:199], v[88:91], v[192:195], v[196:199]


	s_waitcnt lgkmcnt(10)
	v_mfma_f32_16x16x32_bf16 v[196:199], v[120:123], v[148:151], v[196:199]


	s_nop 2
	s_nop 4
	v_cvt_pk_bf16_f32 v196, v196, v197
	v_cvt_pk_bf16_f32 v197, v198, v199
	v_mov_b32_e32 v198, v3
	v_mov_b32_e32 v199, v3
	v_mfma_f32_16x16x32_bf16 v[188:191], v[188:191], v[92:95], 0


	s_nop 0
	v_mfma_f32_16x16x32_bf16 v[196:199], v[0:3], v[196:199], 0


	v_mov_b32_e32 v130, v3
	v_mfma_f32_16x16x32_bf16 v[188:191], v[192:195], v[84:87], v[188:191]
	v_mov_b32_e32 v131, v3
	s_nop 2
	s_nop 1
	v_xor_b32_e32 v102, 0x80000000, v197
	v_xor_b32_e32 v103, 0x80000000, v196
	v_cvt_pk_bf16_f32 v150, v103, v102
	v_xor_b32_e32 v102, 0x80000000, v198
	v_xor_b32_e32 v103, 0x80000000, v199
	v_cvt_pk_bf16_f32 v151, v102, v103


	s_nop 1
	v_mfma_f32_16x16x32_bf16 v[188:191], v[148:151], v[108:111], v[188:191]


	s_waitcnt lgkmcnt(3)
	v_mfma_f32_16x16x32_bf16 v[4:7], v[124:127], v[148:151], v[4:7]
	ds_read_b128 v[140:143], v236 offset:25856
	ds_read_b128 v[136:139], v236 offset:25920
	s_nop 0
	s_nop 2
	v_cvt_pk_bf16_f32 v188, v188, v189
	v_cvt_pk_bf16_f32 v189, v190, v191
	global_store_dwordx2 v[180:181], v[188:189], off offset:32
	s_waitcnt lgkmcnt(4)
	v_mfma_f32_16x16x32_bf16 v[20:23], v[116:119], v[148:151], v[20:23]


	s_waitcnt lgkmcnt(3)
	v_mfma_f32_16x16x32_bf16 v[36:39], v[112:115], v[148:151], v[36:39]


	s_waitcnt lgkmcnt(2)
	v_mfma_f32_16x16x32_bf16 v[48:51], v[104:107], v[148:151], v[48:51]
	v_cvt_pk_bf16_f32 v148, v8, v9
	v_cvt_pk_bf16_f32 v149, v10, v11
	v_cvt_pk_bf16_f32 v150, v24, v25
	v_cvt_pk_bf16_f32 v151, v26, v27
	v_cvt_pk_bf16_f32 v188, v40, v41
	v_cvt_pk_bf16_f32 v189, v42, v43
	v_mfma_f32_16x16x32_bf16 v[192:195], v[96:99], v[148:151], 0
	v_cvt_pk_bf16_f32 v190, v52, v53
	v_cvt_pk_bf16_f32 v191, v54, v55

	v_mfma_f32_16x16x32_bf16 v[148:151], v[148:151], v[92:95], 0
	ds_read_b128 v[132:135], v236 offset:25984
	s_waitcnt lgkmcnt(2)
	v_mul_f32_e32 v6, v142, v6
	v_mul_f32_e32 v7, v143, v7
	v_mul_f32_e32 v4, v140, v4
	v_mul_f32_e32 v5, v141, v5
	v_mfma_f32_16x16x32_bf16 v[192:195], v[88:91], v[188:191], v[192:195]
	s_waitcnt lgkmcnt(1)
	v_mul_f32_e32 v22, v138, v22
	v_mul_f32_e32 v23, v139, v23
	v_mul_f32_e32 v20, v136, v20
	v_mul_f32_e32 v21, v137, v21
	v_mfma_f32_16x16x32_bf16 v[192:195], v[120:123], v[128:131], v[192:195]
	v_mfma_f32_16x16x32_bf16 v[148:151], v[188:191], v[84:87], v[148:151]
	v_mfma_f32_16x16x32_bf16 v[16:19], v[124:127], v[144:147], v[16:19]
	s_nop 5
	v_cvt_pk_bf16_f32 v192, v192, v193
	v_cvt_pk_bf16_f32 v193, v194, v195
	v_mov_b32_e32 v194, v3
	v_mov_b32_e32 v195, v3
	v_mfma_f32_16x16x32_bf16 v[28:31], v[116:119], v[144:147], v[28:31]
	v_mul_f32_e64 v18, v18, v142
	v_mul_f32_e64 v19, v19, v143
	v_mul_f32_e32 v16, v16, v140
	v_mul_f32_e32 v17, v17, v141
	v_mfma_f32_16x16x32_bf16 v[192:195], v[0:3], v[192:195], 0
	v_mfma_f32_16x16x32_bf16 v[32:35], v[112:115], v[144:147], v[32:35]
	s_nop 2
	v_mul_f32_e64 v30, v30, v138
	v_mul_f32_e64 v31, v31, v139
	s_nop 1
	v_xor_b32_e32 v102, 0x80000000, v193
	v_xor_b32_e32 v103, 0x80000000, v192
	v_cvt_pk_bf16_f32 v130, v103, v102
	v_xor_b32_e32 v102, 0x80000000, v194
	v_xor_b32_e32 v103, 0x80000000, v195
	v_cvt_pk_bf16_f32 v131, v102, v103
	v_mov_b32_e32 v103, v3
	v_mfma_f32_16x16x32_bf16 v[56:59], v[104:107], v[144:147], v[56:59]
	ds_read_b128 v[144:147], v236 offset:26048
	v_mul_f32_e32 v28, v28, v136
	v_mul_f32_e32 v29, v29, v137
	s_waitcnt lgkmcnt(1)
	v_mul_f32_e32 v34, v34, v134
	v_mul_f32_e32 v35, v35, v135
	v_mfma_f32_16x16x32_bf16 v[148:151], v[128:131], v[108:111], v[148:151]
	v_mul_f32_e64 v32, v32, v132
	v_mul_f32_e64 v33, v33, v133
	s_waitcnt lgkmcnt(0)
	v_mul_f32_e32 v58, v58, v146
	v_mul_f32_e32 v59, v59, v147
	v_mul_f32_e32 v56, v56, v144
	v_mul_f32_e32 v57, v57, v145
	v_mfma_f32_16x16x32_bf16 v[8:11], v[124:127], v[128:131], v[8:11]
	v_mul_f32_e64 v38, v134, v38
	v_mul_f32_e64 v39, v135, v39
	v_cvt_pk_bf16_f32 v148, v148, v149
	v_cvt_pk_bf16_f32 v149, v150, v151
	global_store_dwordx2 v[180:181], v[148:149], off offset:64

	v_mfma_f32_16x16x32_bf16 v[24:27], v[116:119], v[128:131], v[24:27]


	v_mfma_f32_16x16x32_bf16 v[40:43], v[112:115], v[128:131], v[40:43]


	v_cvt_pk_bf16_f32 v148, v44, v45
	v_mfma_f32_16x16x32_bf16 v[52:55], v[104:107], v[128:131], v[52:55]
	v_cvt_pk_bf16_f32 v128, v12, v13
	v_cvt_pk_bf16_f32 v129, v14, v15
	v_cvt_pk_bf16_f32 v130, v60, v61
	v_cvt_pk_bf16_f32 v131, v62, v63
	v_cvt_pk_bf16_f32 v149, v46, v47
	v_cvt_pk_bf16_f32 v150, v64, v65
	v_mfma_f32_16x16x32_bf16 v[96:99], v[96:99], v[128:131], 0
	v_cvt_pk_bf16_f32 v151, v66, v67

	v_mov_b32_e32 v102, v3
	s_nop 0
	v_mfma_f32_16x16x32_bf16 v[88:91], v[88:91], v[148:151], v[96:99]
	v_mul_f32_e64 v36, v132, v36
	v_mul_f32_e64 v37, v133, v37
	v_mul_f32_e32 v50, v146, v50
	v_mul_f32_e32 v51, v147, v51
	v_mul_f32_e32 v48, v144, v48
	v_mul_f32_e32 v49, v145, v49
	v_mfma_f32_16x16x32_bf16 v[88:91], v[120:123], v[100:103], v[88:91]
	v_mul_f32_e64 v10, v142, v10
	v_mul_f32_e64 v11, v143, v11
	v_mul_f32_e32 v8, v140, v8
	v_mul_f32_e32 v9, v141, v9
	v_mul_f32_e32 v26, v138, v26
	v_mul_f32_e32 v27, v139, v27
	v_mul_f32_e32 v24, v136, v24
	v_mul_f32_e32 v25, v137, v25
	v_mul_f32_e32 v42, v134, v42
	v_mul_f32_e32 v43, v135, v43

	v_cvt_pk_bf16_f32 v88, v88, v89
	v_cvt_pk_bf16_f32 v89, v90, v91
	v_mov_b32_e32 v90, v3
	v_mov_b32_e32 v91, v3
	v_mul_f32_e32 v40, v132, v40
	v_mul_f32_e32 v41, v133, v41
	v_mul_f32_e32 v54, v146, v54
	v_mul_f32_e32 v55, v147, v55
	v_mfma_f32_16x16x32_bf16 v[88:91], v[0:3], v[88:91], 0
	v_mul_f32_e64 v52, v144, v52
	v_mul_f32_e64 v53, v145, v53
	s_nop 5
	v_xor_b32_e32 v0, 0x80000000, v89
	v_xor_b32_e32 v1, 0x80000000, v88
	v_cvt_pk_bf16_f32 v102, v1, v0
	v_xor_b32_e32 v0, 0x80000000, v90
	v_xor_b32_e32 v1, 0x80000000, v91
	v_mfma_f32_16x16x32_bf16 v[88:91], v[128:131], v[92:95], 0
	v_cvt_pk_bf16_f32 v103, v0, v1
	v_mfma_f32_16x16x32_bf16 v[84:87], v[148:151], v[84:87], v[88:91]
	s_nop 0
	v_mfma_f32_16x16x32_bf16 v[84:87], v[100:103], v[108:111], v[84:87]
	v_mfma_f32_16x16x32_bf16 v[12:15], v[124:127], v[100:103], v[12:15]
	v_mfma_f32_16x16x32_bf16 v[60:63], v[116:119], v[100:103], v[60:63]
	s_nop 5
	v_cvt_pk_bf16_f32 v84, v84, v85
	v_cvt_pk_bf16_f32 v85, v86, v87
	global_store_dwordx2 v[180:181], v[84:85], off offset:96


	v_mfma_f32_16x16x32_bf16 v[44:47], v[112:115], v[100:103], v[44:47]


	v_mfma_f32_16x16x32_bf16 v[64:67], v[104:107], v[100:103], v[64:67]

	v_mul_f32_e32 v14, v142, v14
	v_mul_f32_e32 v15, v143, v15
	v_mul_f32_e32 v12, v140, v12
	v_mul_f32_e32 v13, v141, v13
	v_mul_f32_e32 v62, v138, v62
	v_mul_f32_e32 v63, v139, v63
	v_mul_f32_e32 v60, v136, v60
	v_mul_f32_e32 v61, v137, v61
	v_mul_f32_e32 v46, v134, v46
	v_mul_f32_e32 v47, v135, v47
	v_mul_f32_e32 v44, v132, v44
	v_mul_f32_e32 v45, v133, v45

	v_mul_f32_e32 v66, v146, v66
	v_mul_f32_e32 v67, v147, v67
	v_mul_f32_e32 v64, v144, v64
	v_mul_f32_e32 v65, v145, v65

	s_setprio 0
	s_add_i32 s55, s55, 16
	s_add_i32 s54, s54, -16
	s_waitcnt vmcnt(4)
	v_mov_b64_e32 v[86:87], v[82:83]
	s_cmpk_eq_i32 s55, 0x110
	v_mov_b64_e32 v[138:139], v[178:179]
	v_mov_b64_e32 v[136:137], v[170:171]
	v_mov_b64_e32 v[134:135], v[172:173]
	v_mov_b64_e32 v[132:133], v[176:177]
	v_mov_b64_e32 v[124:125], v[174:175]
	v_mov_b64_e32 v[182:183], v[164:165]
	v_mov_b64_e32 v[140:141], v[166:167]
	v_mov_b64_e32 v[0:1], v[168:169]
	v_mov_b64_e32 v[84:85], v[80:81]
	s_cbranch_scc1 .LBB0_527
